# hgin GEMM inner loop hand-scheduled: in-place accumulators, fragment reads up front with next k-step prefetch, counted lgkmcnt waits
# speedup vs baseline: 1.0091x; 1.0077x over previous
; DEV int tidx() { int t = threadIdx.x; asm volatile("" : "+v"(t)); return t; }
; DEV f32x4 mfma16(bf16x8 a, bf16x8 b, f32x4 c) { return __builtin_amdgcn_mfma_f32_16x16x32_bf16(a, b, c, 0, 0, 0); }
; template <int TI, int TJ, int KS>
; DEV void mfma_lds(const bf16_t* Arows, int lda, const bf16_t* Brows, int ldb, int i0, int j0, f32x4 (&acc)[TI][TJ]) {
;   const int lane = tidx() & 63, l15 = lane & 15, quad = lane >> 4;
; #pragma unroll
;   for (int ks = 0; ks < KS; ks++) {
;     bf16x8 af[TI], bfr[TJ];
; #pragma unroll
;     for (int i = 0; i < TI; i++) af[i] = *(const bf16x8*)(Arows + (i0 + i * 16 + l15) * lda + ks * 32 + quad * 8);
; #pragma unroll
;     for (int j = 0; j < TJ; j++) bfr[j] = *(const bf16x8*)(Brows + (j0 + j * 16 + l15) * ldb + ks * 32 + quad * 8);
; #pragma unroll
;     for (int i = 0; i < TI; i++)
; #pragma unroll
;       for (int j = 0; j < TJ; j++) acc[i][j] = mfma16(af[i], bfr[j], acc[i][j]);
;   }
.LBB0_324:
	v_mov_b32_e32 v131, v195
	v_lshl_add_u64 v[132:133], v[132:133], 0, s[34:35]
	v_and_b32_e32 v143, 15, v131
	v_or_b32_e32 v144, v143, v142
	v_and_b32_e32 v148, 48, v131
	v_mul_u32_u24_e32 v131, 0x50, v144
	v_lshl_add_u32 v131, v131, 1, v148
	v_or_b32_e32 v143, v143, v141
	v_mad_u32_u24 v238, v143, s36, v148
	v_lshl_add_u64 v[134:135], v[134:135], 0, s[34:35]
	s_and_b64 vcc, exec, s[6:7]
	ds_read_b128 v[144:147], v131 offset:20480
	ds_read_b128 v[160:163], v238
	ds_read_b128 v[164:167], v238 offset:2560
	ds_read_b128 v[168:171], v238 offset:5120
	ds_read_b128 v[172:175], v238 offset:7680
	ds_read_b128 v[148:151], v131 offset:23040
	ds_read_b128 v[152:155], v131 offset:25600
	ds_read_b128 v[156:159], v131 offset:28160
	ds_read_b128 v[176:179], v238 offset:64
	ds_read_b128 v[180:183], v238 offset:2624
	s_waitcnt lgkmcnt(8)
	v_mfma_f32_16x16x32_bf16 v[62:65], v[144:147], v[160:163], v[62:65]
	s_waitcnt lgkmcnt(7)
	v_mfma_f32_16x16x32_bf16 v[58:61], v[144:147], v[164:167], v[58:61]
	s_waitcnt lgkmcnt(6)
	v_mfma_f32_16x16x32_bf16 v[54:57], v[144:147], v[168:171], v[54:57]
	s_waitcnt lgkmcnt(5)
	v_mfma_f32_16x16x32_bf16 v[50:53], v[144:147], v[172:175], v[50:53]
	ds_read_b128 v[144:147], v131 offset:20544
	s_waitcnt lgkmcnt(5)
	v_mfma_f32_16x16x32_bf16 v[46:49], v[148:151], v[160:163], v[46:49]
	v_mfma_f32_16x16x32_bf16 v[42:45], v[148:151], v[164:167], v[42:45]
	v_mfma_f32_16x16x32_bf16 v[38:41], v[148:151], v[168:171], v[38:41]
	v_mfma_f32_16x16x32_bf16 v[34:37], v[148:151], v[172:175], v[34:37]
	ds_read_b128 v[148:151], v131 offset:23104
	s_waitcnt lgkmcnt(5)
	v_mfma_f32_16x16x32_bf16 v[30:33], v[152:155], v[160:163], v[30:33]
	v_mfma_f32_16x16x32_bf16 v[26:29], v[152:155], v[164:167], v[26:29]
	v_mfma_f32_16x16x32_bf16 v[22:25], v[152:155], v[168:171], v[22:25]
	v_mfma_f32_16x16x32_bf16 v[18:21], v[152:155], v[172:175], v[18:21]
	ds_read_b128 v[152:155], v131 offset:25664
	s_waitcnt lgkmcnt(5)
	v_mfma_f32_16x16x32_bf16 v[6:9], v[156:159], v[168:171], v[6:9]
	v_mfma_f32_16x16x32_bf16 v[2:5], v[156:159], v[172:175], v[2:5]
	ds_read_b128 v[168:171], v238 offset:5184
	ds_read_b128 v[172:175], v238 offset:7744
	v_mfma_f32_16x16x32_bf16 v[14:17], v[156:159], v[160:163], v[14:17]
	v_mfma_f32_16x16x32_bf16 v[10:13], v[156:159], v[164:167], v[10:13]
	ds_read_b128 v[156:159], v131 offset:28224
	s_waitcnt lgkmcnt(5)
	v_mfma_f32_16x16x32_bf16 v[62:65], v[144:147], v[176:179], v[62:65]
	s_waitcnt lgkmcnt(4)
	v_mfma_f32_16x16x32_bf16 v[46:49], v[148:151], v[176:179], v[46:49]
	s_waitcnt lgkmcnt(3)
	v_mfma_f32_16x16x32_bf16 v[30:33], v[152:155], v[176:179], v[30:33]
	v_mfma_f32_16x16x32_bf16 v[58:61], v[144:147], v[180:183], v[58:61]
	v_mfma_f32_16x16x32_bf16 v[42:45], v[148:151], v[180:183], v[42:45]
	v_mfma_f32_16x16x32_bf16 v[26:29], v[152:155], v[180:183], v[26:29]
	s_waitcnt lgkmcnt(2)
	v_mfma_f32_16x16x32_bf16 v[54:57], v[144:147], v[168:171], v[54:57]
	v_mfma_f32_16x16x32_bf16 v[38:41], v[148:151], v[168:171], v[38:41]
	v_mfma_f32_16x16x32_bf16 v[22:25], v[152:155], v[168:171], v[22:25]
	s_waitcnt lgkmcnt(1)
	v_mfma_f32_16x16x32_bf16 v[50:53], v[144:147], v[172:175], v[50:53]
	v_mfma_f32_16x16x32_bf16 v[34:37], v[148:151], v[172:175], v[34:37]
	v_mfma_f32_16x16x32_bf16 v[18:21], v[152:155], v[172:175], v[18:21]
	s_waitcnt lgkmcnt(0)
	v_mfma_f32_16x16x32_bf16 v[14:17], v[156:159], v[176:179], v[14:17]
	v_mfma_f32_16x16x32_bf16 v[10:13], v[156:159], v[180:183], v[10:13]
	v_mfma_f32_16x16x32_bf16 v[6:9], v[156:159], v[168:171], v[6:9]
	v_mfma_f32_16x16x32_bf16 v[2:5], v[156:159], v[172:175], v[2:5]
	s_cbranch_vccnz .LBB0_329

; DEV f32x4 mfma16(bf16x8 a, bf16x8 b, f32x4 c) { return __builtin_amdgcn_mfma_f32_16x16x32_bf16(a, b, c, 0, 0, 0); }
; #define G_LOAD(RA, RB, KT) { _Pragma("unroll") for (int i = 0; i < 4; i++) { \
;       RA[i] = *(const u32x4*)(Ap + (size_t)(i * 32) * lda + (KT) * 64); RB[i] = *(const u32x4*)(Bp + (size_t)(i * 32) * ldb + (KT) * 64); } }
; #define G_STORE(RA, RB) { _Pragma("unroll") for (int i = 0; i < 4; i++) { \
;       *(u32x4*)(As + (lrow + i * 32) * GLD + lcc * 8) = RA[i]; *(u32x4*)(Bs + (lrow + i * 32) * GLD + lcc * 8) = RB[i]; } }
; template <int TI, int TJ, int KS>
; DEV void mfma_lds(const bf16_t* Arows, int lda, const bf16_t* Brows, int ldb, int i0, int j0, f32x4 (&acc)[TI][TJ]) {
;     ...
;   for (int ks = 0; ks < KS; ks++) {
;     bf16x8 af[TI], bfr[TJ];
; #pragma unroll
;     for (int i = 0; i < TI; i++) af[i] = *(const bf16x8*)(Arows + (i0 + i * 16 + l15) * lda + ks * 32 + quad * 8);
; #pragma unroll
;     for (int j = 0; j < TJ; j++) bfr[j] = *(const bf16x8*)(Brows + (j0 + j * 16 + l15) * ldb + ks * 32 + quad * 8);
; #pragma unroll
;     for (int i = 0; i < TI; i++)
; #pragma unroll
;       for (int j = 0; j < TJ; j++) acc[i][j] = mfma16(af[i], bfr[j], acc[i][j]);
;   }
; template <class Epi>
; DEV void gemm_tile(const bf16_t* __restrict__ A, int lda, const bf16_t* __restrict__ Bt, int ldb, int K, int m0, int n0,
;                    Epi& epi, char* smem) {
;     ...
;   for (int kt = 0; kt < nk; kt += 2) {
;     __syncthreads();
;     G_STORE(ra0, rb0);
;     __syncthreads();
;     if (kt + 2 < nk) G_LOAD(ra0, rb0, kt + 2);
;     mfma_lds<4, 4, 2>(Bs, GLD, As, GLD, wn * 64, wm * 64, acc);
;     __syncthreads();
;     G_STORE(ra1, rb1);
;     __syncthreads();
;     if (kt + 3 < nk) G_LOAD(ra1, rb1, kt + 3);
;     mfma_lds<4, 4, 2>(Bs, GLD, As, GLD, wn * 64, wm * 64, acc);
;   }
.LBB0_327:
	v_mov_b32_e32 v131, v195
	s_cmp_gt_u32 s1, 12
	v_and_b32_e32 v143, 15, v131
	v_or_b32_e32 v144, v143, v142
	v_and_b32_e32 v148, 48, v131
	v_mul_u32_u24_e32 v131, 0x50, v144
	v_lshl_add_u32 v131, v131, 1, v148
	v_or_b32_e32 v143, v143, v141
	v_mad_u32_u24 v238, v143, s36, v148
	ds_read_b128 v[144:147], v131 offset:20480
	ds_read_b128 v[160:163], v238
	ds_read_b128 v[164:167], v238 offset:2560
	ds_read_b128 v[168:171], v238 offset:5120
	ds_read_b128 v[172:175], v238 offset:7680
	ds_read_b128 v[148:151], v131 offset:23040
	ds_read_b128 v[152:155], v131 offset:25600
	ds_read_b128 v[156:159], v131 offset:28160
	ds_read_b128 v[176:179], v238 offset:64
	ds_read_b128 v[180:183], v238 offset:2624
	s_waitcnt lgkmcnt(8)
	v_mfma_f32_16x16x32_bf16 v[62:65], v[144:147], v[160:163], v[62:65]
	s_waitcnt lgkmcnt(7)
	v_mfma_f32_16x16x32_bf16 v[58:61], v[144:147], v[164:167], v[58:61]
	s_waitcnt lgkmcnt(6)
	v_mfma_f32_16x16x32_bf16 v[54:57], v[144:147], v[168:171], v[54:57]
	s_waitcnt lgkmcnt(5)
	v_mfma_f32_16x16x32_bf16 v[50:53], v[144:147], v[172:175], v[50:53]
	ds_read_b128 v[144:147], v131 offset:20544
	s_waitcnt lgkmcnt(5)
	v_mfma_f32_16x16x32_bf16 v[46:49], v[148:151], v[160:163], v[46:49]
	v_mfma_f32_16x16x32_bf16 v[42:45], v[148:151], v[164:167], v[42:45]
	v_mfma_f32_16x16x32_bf16 v[38:41], v[148:151], v[168:171], v[38:41]
	v_mfma_f32_16x16x32_bf16 v[34:37], v[148:151], v[172:175], v[34:37]
	ds_read_b128 v[148:151], v131 offset:23104
	s_waitcnt lgkmcnt(5)
	v_mfma_f32_16x16x32_bf16 v[30:33], v[152:155], v[160:163], v[30:33]
	v_mfma_f32_16x16x32_bf16 v[26:29], v[152:155], v[164:167], v[26:29]
	v_mfma_f32_16x16x32_bf16 v[22:25], v[152:155], v[168:171], v[22:25]
	v_mfma_f32_16x16x32_bf16 v[18:21], v[152:155], v[172:175], v[18:21]
	ds_read_b128 v[152:155], v131 offset:25664
	s_waitcnt lgkmcnt(5)
	v_mfma_f32_16x16x32_bf16 v[6:9], v[156:159], v[168:171], v[6:9]
	v_mfma_f32_16x16x32_bf16 v[2:5], v[156:159], v[172:175], v[2:5]
	ds_read_b128 v[168:171], v238 offset:5184
	ds_read_b128 v[172:175], v238 offset:7744
	v_mfma_f32_16x16x32_bf16 v[14:17], v[156:159], v[160:163], v[14:17]
	v_mfma_f32_16x16x32_bf16 v[10:13], v[156:159], v[164:167], v[10:13]
	ds_read_b128 v[156:159], v131 offset:28224
	s_waitcnt lgkmcnt(5)
	v_mfma_f32_16x16x32_bf16 v[62:65], v[144:147], v[176:179], v[62:65]
	s_waitcnt lgkmcnt(4)
	v_mfma_f32_16x16x32_bf16 v[46:49], v[148:151], v[176:179], v[46:49]
	s_waitcnt lgkmcnt(3)
	v_mfma_f32_16x16x32_bf16 v[30:33], v[152:155], v[176:179], v[30:33]
	v_mfma_f32_16x16x32_bf16 v[58:61], v[144:147], v[180:183], v[58:61]
	v_mfma_f32_16x16x32_bf16 v[42:45], v[148:151], v[180:183], v[42:45]
	v_mfma_f32_16x16x32_bf16 v[26:29], v[152:155], v[180:183], v[26:29]
	s_waitcnt lgkmcnt(2)
	v_mfma_f32_16x16x32_bf16 v[54:57], v[144:147], v[168:171], v[54:57]
	v_mfma_f32_16x16x32_bf16 v[38:41], v[148:151], v[168:171], v[38:41]
	v_mfma_f32_16x16x32_bf16 v[22:25], v[152:155], v[168:171], v[22:25]
	s_waitcnt lgkmcnt(1)
	v_mfma_f32_16x16x32_bf16 v[50:53], v[144:147], v[172:175], v[50:53]
	v_mfma_f32_16x16x32_bf16 v[34:37], v[148:151], v[172:175], v[34:37]
	v_mfma_f32_16x16x32_bf16 v[18:21], v[152:155], v[172:175], v[18:21]
	s_waitcnt lgkmcnt(0)
	v_mfma_f32_16x16x32_bf16 v[14:17], v[156:159], v[176:179], v[14:17]
	s_barrier
	v_mfma_f32_16x16x32_bf16 v[10:13], v[156:159], v[180:183], v[10:13]
	s_waitcnt vmcnt(8)
	ds_write_b128 v130, v[70:73]
	ds_write_b128 v130, v[78:81] offset:20480
	ds_write_b128 v130, v[86:89] offset:5120
	ds_write_b128 v130, v[94:97] offset:25600
	ds_write_b128 v130, v[102:105] offset:10240
	ds_write_b128 v130, v[110:113] offset:30720
	ds_write_b128 v130, v[118:121] offset:15360
	ds_write_b128 v130, v[126:129] offset:35840
	v_mfma_f32_16x16x32_bf16 v[6:9], v[156:159], v[168:171], v[6:9]
	s_waitcnt lgkmcnt(0)
	s_barrier
	v_mfma_f32_16x16x32_bf16 v[2:5], v[156:159], v[172:175], v[2:5]
	s_cbranch_scc1 .LBB0_324
	v_add_co_u32_e32 v70, vcc, 0x4200000, v138
	s_nop 1
	v_addc_co_u32_e32 v71, vcc, 0, v139, vcc
	v_add_co_u32_e32 v78, vcc, 0xa900000, v136
	global_load_dwordx4 v[70:73], v[70:71], off offset:384
	s_nop 0
	v_addc_co_u32_e32 v79, vcc, 0, v137, vcc
	v_add_co_u32_e32 v86, vcc, 0x4211000, v138
	global_load_dwordx4 v[78:81], v[78:79], off offset:384
	s_nop 0
	v_addc_co_u32_e32 v87, vcc, 0, v139, vcc
	v_add_co_u32_e32 v94, vcc, 0xa911000, v136
	global_load_dwordx4 v[86:89], v[86:87], off offset:384
	s_nop 0
	v_addc_co_u32_e32 v95, vcc, 0, v137, vcc
	v_add_co_u32_e32 v102, vcc, 0x4222000, v138
	global_load_dwordx4 v[94:97], v[94:95], off offset:384
	s_nop 0
	v_addc_co_u32_e32 v103, vcc, 0, v139, vcc
	v_add_co_u32_e32 v110, vcc, 0xa922000, v136
	global_load_dwordx4 v[102:105], v[102:103], off offset:384
	s_nop 0
	v_addc_co_u32_e32 v111, vcc, 0, v137, vcc
	v_add_co_u32_e32 v118, vcc, 0x4233000, v138
	global_load_dwordx4 v[110:113], v[110:111], off offset:384
	s_nop 0
	v_addc_co_u32_e32 v119, vcc, 0, v139, vcc
	v_add_co_u32_e32 v126, vcc, 0xa933000, v136
	global_load_dwordx4 v[118:121], v[118:119], off offset:384
	s_nop 0
	v_addc_co_u32_e32 v127, vcc, 0, v137, vcc
	global_load_dwordx4 v[126:129], v[126:127], off offset:384
	s_branch .LBB0_324

; DEV unsigned pack2(float a, float b) { f32x2 v = {a, b}; return __builtin_bit_cast(unsigned, __builtin_convertvector(v, bf2_t)); }
; DEV float sigm(float x) { return 1.f / (1.f + __expf(-x)); }
;   DEV void operator()(int m, int n, f32x4 v) {
;     const int seg = n >> 10, c = n & 1023;
;     bf16_t* dst;
;     if (seg == 0) dst = QH; else if (seg == 1) dst = LF; else if (seg == 2) dst = LB; else if (seg == 3) dst = IH; else dst = GH;
;     if (seg == 1 || seg == 2) {
;       const int dir = seg - 1;
; #pragma unroll
;       for (int r = 0; r < 4; r++) {
;         float lb = sigm(lbp[(2 + dir) * 1024 + c + r] - lbp[dir * 1024 + c + r]);
;         float ff = lb + (1.f - lb) * sigm(v[r]);
;         v[r] = __logf(ff);
;       }
;     }
;     uint2 o; o.x = pack2(v[0], v[1]); o.y = pack2(v[2], v[3]);
;     *(uint2*)(dst + (size_t)m * 1024 + c) = o;
.LBB0_329:
	s_nop 7
	s_nop 7
	s_ashr_i32 s22, s0, 3
	s_cmpk_gt_u32 s13, 0x3ff
	s_cselect_b64 s[6:7], -1, 0
	s_and_b64 vcc, exec, s[6:7]
	s_mov_b64 s[14:15], s[44:45]
	s_cbranch_vccz .LBB0_342
	s_cmp_lt_i32 s22, 2
	s_cbranch_scc1 .LBB0_335
	s_cmp_gt_i32 s22, 2
	s_cbranch_scc0 .LBB0_336
	s_cmp_eq_u32 s22, 3
	s_mov_b64 s[0:1], -1
	s_cbranch_scc0 .LBB0_334
	s_mov_b64 s[0:1], 0
